# EpiAct epilogues (both W1 GEMMs): waves pool their 16-column bf16 blocks in LDS (xor-swizzled) and store full 128-byte lines (8 dwordx4 instead of 16 dwordx2 per wave); + P4 5th-round tile remap
# speedup vs baseline: 1.0183x; 1.0183x over previous
; #define WAIT_V(n) asm volatile("s_waitcnt vmcnt(" #n ")" ::: "memory")
; template <class Epi>
; DEVI void gemm_phase(const Params& p, const u16* __restrict__ A, const u16* __restrict__ Bt, const int M, const int N, const int K, const int Msplit, const Epi& epi) {
;     ...
;     if (it == 0) { WAIT_V(0); } else { if constexpr (Epi::NST == 16) WAIT_V(16); else if constexpr (Epi::NST == 32) WAIT_V(32); else WAIT_V(0); }
.LBB0_677:
	s_cmp_lg_u32 s18, 0
	s_cbranch_scc0 .LBB0_738
	s_waitcnt vmcnt(8)
	s_cbranch_execnz .LBB0_680

; DEVI unsigned pk_bf16(float lo, float hi) { unsigned r; asm volatile("v_cvt_pk_bf16_f32 %0, %1, %2" : "=v"(r) : "v"(lo), "v"(hi)); return r; }
; DEVI float sigmoidf_(float x) { return __builtin_amdgcn_rcpf(1.f + __expf(-x)); }
; template <class Epi>
; DEVI void gemm_phase(const Params& p, const u16* __restrict__ A, const u16* __restrict__ Bt, const int M, const int N, const int K, const int Msplit, const Epi& epi) {
;     ...
; #pragma unroll
;       for (int ai = 0; ai < 2; ++ai)
; #pragma unroll
;         for (int bj = 0; bj < 2; ++bj) {
;           const int colb = bcol + bj * HALF + wc2 * 32;
;           typename Epi::Pre pre;
;           if constexpr (Epi::NRM || Epi::SQ) epi.preload(pre, brow, colb, wr2, fr2, fq2, nrm, slcur);
; #pragma unroll
;           for (int m = 0; m < 4; ++m) {
;             const int rloc = ai * HALF + wr2 * 64 + m * 16;
;             if constexpr (Epi::SQ) epi(brow + rloc + fr2, colb, fq2, acc[ai][bj][m][0], acc[ai][bj][m][1], sq[ai * 4 + m], slcur, pre);
;             else if constexpr (Epi::TR) { float rv = 1.f; if (nrm) rv = rl[rloc + fr2]; epi(brow + rloc + fr2, colb, fq2, acc[ai][bj][m][0], acc[ai][bj][m][1], rv, nrm, pre); }
;             else { f32x4 rv = {1.f, 1.f, 1.f, 1.f}; if (nrm) rv = *(const f32x4*)(rl + rloc + fq2 * 4); epi(brow + rloc + fq2 * 4, colb, fr2, acc[ai][bj][m][0], acc[ai][bj][m][1], rv, nrm, pre); }
;   DEVI void operator()(int row, int colb, int fq, const f32x4& a0, const f32x4& a1, const float rinv, const bool nrm, const Pre& q) const {
;     const int oc = (colb >> 5) * 16 + 4 * fq;
;     f32x4 xa = a0, xb = a1;
;     if (nrm) {
; #pragma unroll
;       for (int j = 0; j < 4; ++j) { xa[j] = xa[j] * rinv + q.sa[j]; xb[j] = xb[j] * rinv + q.sb[j]; }
;     }
;     float v[4];
; #pragma unroll
;     for (int j = 0; j < 4; ++j) { const float a = xa[j]; v[j] = a * sigmoidf_(a) * xb[j]; }
;     uint2 o; o.x = pk_bf16(v[0], v[1]); o.y = pk_bf16(v[2], v[3]);
;     *(uint2*)(act + (size_t)row * DFF + oc) = o;
.Lmy_p2_epi:
	v_mbcnt_lo_u32_b32 v200, -1, 0
	v_mbcnt_hi_u32_b32 v200, -1, v200
	s_lshr_b32 s52, s33, 6
	s_lshr_b32 s53, s52, 2
	s_and_b32 s54, s52, 3
	v_and_b32_e32 v201, 15, v200
	v_lshrrev_b32_e32 v144, 4, v200
	v_lshrrev_b32_e32 v145, 1, v144
	s_lshl_b32 s55, s54, 1
	v_or_b32_e32 v145, s55, v145
	v_and_b32_e32 v146, 7, v201
	v_xor_b32_e32 v145, v145, v146
	v_lshlrev_b32_e32 v145, 4, v145
	v_and_b32_e32 v146, 1, v144
	v_lshl_or_b32 v145, v146, 3, v145
	s_lshl_b32 s55, s53, 6
	v_add_u32_e32 v146, s55, v201
	v_lshl_add_u32 v192, v146, 7, v145
	v_add_u32_e32 v193, 0x20000, v192
	v_and_b32_e32 v147, 7, v200
	v_lshrrev_b32_e32 v150, 3, v200
	v_xor_b32_e32 v145, v147, v150
	v_lshlrev_b32_e32 v145, 4, v145
	s_lshl_b32 s55, s52, 4
	v_add_u32_e32 v146, s55, v150
	v_lshl_add_u32 v194, v146, 7, v145
	v_add_u32_e32 v195, 0x20000, v194
	v_mul_u32_u24_e32 v146, 0x1600, v146
	v_lshl_add_u32 v148, v147, 4, v146
	v_add_u32_e32 v149, 0xb000, v148
	s_lshl_b32 s55, s53, 8
	v_lshl_add_u32 v203, v201, 2, s55
	v_lshlrev_b32_e32 v202, 4, v144
	s_lshl_b32 s55, s54, 7
	v_add_u32_e32 v202, s55, v202
	v_mov_b32_e32 v196, 1.0
	v_mov_b32_e32 v197, 1.0
	v_mov_b32_e32 v198, 0xbfb8aa3b
	v_mov_b32_e32 v199, 0xbfb8aa3b
	s_mul_i32 s54, s90, 0x1600
	s_add_u32 s54, s54, s18
	s_add_u32 s44, s60, s54
	s_addc_u32 s45, s61, 0
	s_add_u32 s46, s44, 0xb0000
	s_addc_u32 s47, s45, 0
	s_and_b64 vcc, exec, s[12:13]
	s_cbranch_vccz .Lmy_p2_plain
	v_readlane_b32 s56, v253, 49
	v_readlane_b32 s57, v253, 50
	s_lshr_b32 s54, s16, 4
	s_mul_i32 s54, s54, 0x5800
	s_lshl_b32 s55, s18, 2
	s_add_u32 s54, s54, s55
	s_add_u32 s56, s56, s54
	s_addc_u32 s57, s57, 0
	global_load_dwordx4 v[152:155], v202, s[56:57]
	global_load_dwordx4 v[156:159], v202, s[56:57] offset:64
	global_load_dwordx4 v[160:163], v202, s[56:57] offset:512
	global_load_dwordx4 v[164:167], v202, s[56:57] offset:576
	ds_read_b32 v168, v203 offset:49152
	ds_read_b32 v169, v203 offset:49216
	ds_read_b32 v170, v203 offset:49280
	ds_read_b32 v171, v203 offset:49344
	ds_read_b32 v172, v203 offset:49664
	ds_read_b32 v173, v203 offset:49728
	ds_read_b32 v174, v203 offset:49792
	ds_read_b32 v175, v203 offset:49856
	s_waitcnt vmcnt(0) lgkmcnt(0)
	v_fma_f32 v128, v128, v168, v152
	v_fma_f32 v129, v129, v168, v153
	v_fma_f32 v130, v130, v168, v154
	v_fma_f32 v131, v131, v168, v155
	v_fma_f32 v132, v132, v168, v156
	v_fma_f32 v133, v133, v168, v157
	v_fma_f32 v134, v134, v168, v158
	v_fma_f32 v135, v135, v168, v159
	v_fma_f32 v120, v120, v169, v152
	v_fma_f32 v121, v121, v169, v153
	v_fma_f32 v122, v122, v169, v154
	v_fma_f32 v123, v123, v169, v155
	v_fma_f32 v124, v124, v169, v156
	v_fma_f32 v125, v125, v169, v157
	v_fma_f32 v126, v126, v169, v158
	v_fma_f32 v127, v127, v169, v159
	v_fma_f32 v112, v112, v170, v152
	v_fma_f32 v113, v113, v170, v153
	v_fma_f32 v114, v114, v170, v154
	v_fma_f32 v115, v115, v170, v155
	v_fma_f32 v116, v116, v170, v156
	v_fma_f32 v117, v117, v170, v157
	v_fma_f32 v118, v118, v170, v158
	v_fma_f32 v119, v119, v170, v159
	v_fma_f32 v104, v104, v171, v152
	v_fma_f32 v105, v105, v171, v153
	v_fma_f32 v106, v106, v171, v154
	v_fma_f32 v107, v107, v171, v155
	v_fma_f32 v108, v108, v171, v156
	v_fma_f32 v109, v109, v171, v157
	v_fma_f32 v110, v110, v171, v158
	v_fma_f32 v111, v111, v171, v159
	v_fma_f32 v96, v96, v168, v160
	v_fma_f32 v97, v97, v168, v161
	v_fma_f32 v98, v98, v168, v162
	v_fma_f32 v99, v99, v168, v163
	v_fma_f32 v100, v100, v168, v164
	v_fma_f32 v101, v101, v168, v165
	v_fma_f32 v102, v102, v168, v166
	v_fma_f32 v103, v103, v168, v167
	v_fma_f32 v88, v88, v169, v160
	v_fma_f32 v89, v89, v169, v161
	v_fma_f32 v90, v90, v169, v162
	v_fma_f32 v91, v91, v169, v163
	v_fma_f32 v92, v92, v169, v164
	v_fma_f32 v93, v93, v169, v165
	v_fma_f32 v94, v94, v169, v166
	v_fma_f32 v95, v95, v169, v167
	v_fma_f32 v80, v80, v170, v160
	v_fma_f32 v81, v81, v170, v161
	v_fma_f32 v82, v82, v170, v162
	v_fma_f32 v83, v83, v170, v163
	v_fma_f32 v84, v84, v170, v164
	v_fma_f32 v85, v85, v170, v165
	v_fma_f32 v86, v86, v170, v166
	v_fma_f32 v87, v87, v170, v167
	v_fma_f32 v72, v72, v171, v160
	v_fma_f32 v73, v73, v171, v161
	v_fma_f32 v74, v74, v171, v162
	v_fma_f32 v75, v75, v171, v163
	v_fma_f32 v76, v76, v171, v164
	v_fma_f32 v77, v77, v171, v165
	v_fma_f32 v78, v78, v171, v166
	v_fma_f32 v79, v79, v171, v167
	v_fma_f32 v64, v64, v172, v152
	v_fma_f32 v65, v65, v172, v153
	v_fma_f32 v66, v66, v172, v154
	v_fma_f32 v67, v67, v172, v155
	v_fma_f32 v68, v68, v172, v156
	v_fma_f32 v69, v69, v172, v157
	v_fma_f32 v70, v70, v172, v158
	v_fma_f32 v71, v71, v172, v159
	v_fma_f32 v56, v56, v173, v152
	v_fma_f32 v57, v57, v173, v153
	v_fma_f32 v58, v58, v173, v154
	v_fma_f32 v59, v59, v173, v155
	v_fma_f32 v60, v60, v173, v156
	v_fma_f32 v61, v61, v173, v157
	v_fma_f32 v62, v62, v173, v158
	v_fma_f32 v63, v63, v173, v159
	v_fma_f32 v48, v48, v174, v152
	v_fma_f32 v49, v49, v174, v153
	v_fma_f32 v50, v50, v174, v154
	v_fma_f32 v51, v51, v174, v155
	v_fma_f32 v52, v52, v174, v156
	v_fma_f32 v53, v53, v174, v157
	v_fma_f32 v54, v54, v174, v158
	v_fma_f32 v55, v55, v174, v159
	v_fma_f32 v40, v40, v175, v152
	v_fma_f32 v41, v41, v175, v153
	v_fma_f32 v42, v42, v175, v154
	v_fma_f32 v43, v43, v175, v155
	v_fma_f32 v44, v44, v175, v156
	v_fma_f32 v45, v45, v175, v157
	v_fma_f32 v46, v46, v175, v158
	v_fma_f32 v47, v47, v175, v159
	v_fma_f32 v32, v32, v172, v160
	v_fma_f32 v33, v33, v172, v161
	v_fma_f32 v34, v34, v172, v162
	v_fma_f32 v35, v35, v172, v163
	v_fma_f32 v36, v36, v172, v164
	v_fma_f32 v37, v37, v172, v165
	v_fma_f32 v38, v38, v172, v166
	v_fma_f32 v39, v39, v172, v167
	v_fma_f32 v24, v24, v173, v160
	v_fma_f32 v25, v25, v173, v161
	v_fma_f32 v26, v26, v173, v162
	v_fma_f32 v27, v27, v173, v163
	v_fma_f32 v28, v28, v173, v164
	v_fma_f32 v29, v29, v173, v165
	v_fma_f32 v30, v30, v173, v166
	v_fma_f32 v31, v31, v173, v167
	v_fma_f32 v16, v16, v174, v160
	v_fma_f32 v17, v17, v174, v161
	v_fma_f32 v18, v18, v174, v162
	v_fma_f32 v19, v19, v174, v163
	v_fma_f32 v20, v20, v174, v164
	v_fma_f32 v21, v21, v174, v165
	v_fma_f32 v22, v22, v174, v166
	v_fma_f32 v23, v23, v174, v167
	v_fma_f32 v8, v8, v175, v160
	v_fma_f32 v9, v9, v175, v161
	v_fma_f32 v10, v10, v175, v162
	v_fma_f32 v11, v11, v175, v163
	v_fma_f32 v12, v12, v175, v164
	v_fma_f32 v13, v13, v175, v165
	v_fma_f32 v14, v14, v175, v166
	v_fma_f32 v15, v15, v175, v167
; DEVI unsigned pk_bf16(float lo, float hi) { unsigned r; asm volatile("v_cvt_pk_bf16_f32 %0, %1, %2" : "=v"(r) : "v"(lo), "v"(hi)); return r; }
; DEVI float sigmoidf_(float x) { return __builtin_amdgcn_rcpf(1.f + __expf(-x)); }
;   DEVI void operator()(int row, int colb, int fq, const f32x4& a0, const f32x4& a1, const float rinv, const bool nrm, const Pre& q) const {
;     ...
;     float v[4];
; #pragma unroll
;     for (int j = 0; j < 4; ++j) { const float a = xa[j]; v[j] = a * sigmoidf_(a) * xb[j]; }
;     uint2 o; o.x = pk_bf16(v[0], v[1]); o.y = pk_bf16(v[2], v[3]);
;     *(uint2*)(act + (size_t)row * DFF + oc) = o;
.Lmy_p2_plain:
	v_pk_mul_f32 v[176:177], v[128:129], v[198:199]
	v_pk_mul_f32 v[178:179], v[130:131], v[198:199]
	v_pk_mul_f32 v[184:185], v[120:121], v[198:199]
	v_pk_mul_f32 v[186:187], v[122:123], v[198:199]
	v_exp_f32_e32 v176, v176
	v_exp_f32_e32 v177, v177
	v_exp_f32_e32 v178, v178
	v_exp_f32_e32 v179, v179
	v_exp_f32_e32 v184, v184
	v_exp_f32_e32 v185, v185
	v_exp_f32_e32 v186, v186
	v_exp_f32_e32 v187, v187
	v_pk_add_f32 v[176:177], v[196:197], v[176:177]
	v_pk_add_f32 v[178:179], v[196:197], v[178:179]
	v_pk_add_f32 v[184:185], v[196:197], v[184:185]
	v_pk_add_f32 v[186:187], v[196:197], v[186:187]
	v_rcp_f32_e32 v176, v176
	v_rcp_f32_e32 v177, v177
	v_rcp_f32_e32 v178, v178
	v_rcp_f32_e32 v179, v179
	v_rcp_f32_e32 v184, v184
	v_rcp_f32_e32 v185, v185
	v_rcp_f32_e32 v186, v186
	v_rcp_f32_e32 v187, v187
	v_pk_mul_f32 v[128:129], v[128:129], v[176:177]
	v_pk_mul_f32 v[130:131], v[130:131], v[178:179]
	v_pk_mul_f32 v[120:121], v[120:121], v[184:185]
	v_pk_mul_f32 v[122:123], v[122:123], v[186:187]
	v_pk_mul_f32 v[128:129], v[132:133], v[128:129]
	v_pk_mul_f32 v[130:131], v[134:135], v[130:131]
	v_pk_mul_f32 v[120:121], v[124:125], v[120:121]
	v_pk_mul_f32 v[122:123], v[126:127], v[122:123]
	v_cvt_pk_bf16_f32 v132, v128, v129
	v_cvt_pk_bf16_f32 v133, v130, v131
	v_cvt_pk_bf16_f32 v124, v120, v121
	v_cvt_pk_bf16_f32 v125, v122, v123
	v_pk_mul_f32 v[176:177], v[112:113], v[198:199]
	v_pk_mul_f32 v[178:179], v[114:115], v[198:199]
	v_pk_mul_f32 v[184:185], v[104:105], v[198:199]
	v_pk_mul_f32 v[186:187], v[106:107], v[198:199]
	v_exp_f32_e32 v176, v176
	v_exp_f32_e32 v177, v177
	v_exp_f32_e32 v178, v178
	v_exp_f32_e32 v179, v179
	v_exp_f32_e32 v184, v184
	v_exp_f32_e32 v185, v185
	v_exp_f32_e32 v186, v186
	v_exp_f32_e32 v187, v187
	v_pk_add_f32 v[176:177], v[196:197], v[176:177]
	v_pk_add_f32 v[178:179], v[196:197], v[178:179]
	v_pk_add_f32 v[184:185], v[196:197], v[184:185]
	v_pk_add_f32 v[186:187], v[196:197], v[186:187]
	v_rcp_f32_e32 v176, v176
	v_rcp_f32_e32 v177, v177
	v_rcp_f32_e32 v178, v178
	v_rcp_f32_e32 v179, v179
	v_rcp_f32_e32 v184, v184
	v_rcp_f32_e32 v185, v185
	v_rcp_f32_e32 v186, v186
	v_rcp_f32_e32 v187, v187
	v_pk_mul_f32 v[112:113], v[112:113], v[176:177]
	v_pk_mul_f32 v[114:115], v[114:115], v[178:179]
	v_pk_mul_f32 v[104:105], v[104:105], v[184:185]
	v_pk_mul_f32 v[106:107], v[106:107], v[186:187]
	v_pk_mul_f32 v[112:113], v[116:117], v[112:113]
	v_pk_mul_f32 v[114:115], v[118:119], v[114:115]
	v_pk_mul_f32 v[104:105], v[108:109], v[104:105]
	v_pk_mul_f32 v[106:107], v[110:111], v[106:107]
	v_cvt_pk_bf16_f32 v116, v112, v113
	v_cvt_pk_bf16_f32 v117, v114, v115
	v_cvt_pk_bf16_f32 v108, v104, v105
	v_cvt_pk_bf16_f32 v109, v106, v107
	ds_write_b64 v193, v[132:133]
	ds_write_b64 v193, v[124:125] offset:2048
	ds_write_b64 v193, v[116:117] offset:4096
	ds_write_b64 v193, v[108:109] offset:6144
	v_pk_mul_f32 v[176:177], v[96:97], v[198:199]
	v_pk_mul_f32 v[178:179], v[98:99], v[198:199]
	v_pk_mul_f32 v[184:185], v[88:89], v[198:199]
	v_pk_mul_f32 v[186:187], v[90:91], v[198:199]
	v_exp_f32_e32 v176, v176
	v_exp_f32_e32 v177, v177
	v_exp_f32_e32 v178, v178
	v_exp_f32_e32 v179, v179
	v_exp_f32_e32 v184, v184
	v_exp_f32_e32 v185, v185
	v_exp_f32_e32 v186, v186
	v_exp_f32_e32 v187, v187
	v_pk_add_f32 v[176:177], v[196:197], v[176:177]
	v_pk_add_f32 v[178:179], v[196:197], v[178:179]
	v_pk_add_f32 v[184:185], v[196:197], v[184:185]
	v_pk_add_f32 v[186:187], v[196:197], v[186:187]
	v_rcp_f32_e32 v176, v176
	v_rcp_f32_e32 v177, v177
	v_rcp_f32_e32 v178, v178
	v_rcp_f32_e32 v179, v179
	v_rcp_f32_e32 v184, v184
	v_rcp_f32_e32 v185, v185
	v_rcp_f32_e32 v186, v186
	v_rcp_f32_e32 v187, v187
	v_pk_mul_f32 v[96:97], v[96:97], v[176:177]
	v_pk_mul_f32 v[98:99], v[98:99], v[178:179]
	v_pk_mul_f32 v[88:89], v[88:89], v[184:185]
	v_pk_mul_f32 v[90:91], v[90:91], v[186:187]
	v_pk_mul_f32 v[96:97], v[100:101], v[96:97]
	v_pk_mul_f32 v[98:99], v[102:103], v[98:99]
	v_pk_mul_f32 v[88:89], v[92:93], v[88:89]
	v_pk_mul_f32 v[90:91], v[94:95], v[90:91]
	v_cvt_pk_bf16_f32 v100, v96, v97
	v_cvt_pk_bf16_f32 v101, v98, v99
	v_cvt_pk_bf16_f32 v92, v88, v89
	v_cvt_pk_bf16_f32 v93, v90, v91
	v_pk_mul_f32 v[176:177], v[80:81], v[198:199]
	v_pk_mul_f32 v[178:179], v[82:83], v[198:199]
	v_pk_mul_f32 v[184:185], v[72:73], v[198:199]
	v_pk_mul_f32 v[186:187], v[74:75], v[198:199]
	v_exp_f32_e32 v176, v176
	v_exp_f32_e32 v177, v177
	v_exp_f32_e32 v178, v178
	v_exp_f32_e32 v179, v179
	v_exp_f32_e32 v184, v184
	v_exp_f32_e32 v185, v185
	v_exp_f32_e32 v186, v186
	v_exp_f32_e32 v187, v187
	v_pk_add_f32 v[176:177], v[196:197], v[176:177]
	v_pk_add_f32 v[178:179], v[196:197], v[178:179]
	v_pk_add_f32 v[184:185], v[196:197], v[184:185]
	v_pk_add_f32 v[186:187], v[196:197], v[186:187]
	v_rcp_f32_e32 v176, v176
	v_rcp_f32_e32 v177, v177
	v_rcp_f32_e32 v178, v178
	v_rcp_f32_e32 v179, v179
	v_rcp_f32_e32 v184, v184
	v_rcp_f32_e32 v185, v185
	v_rcp_f32_e32 v186, v186
	v_rcp_f32_e32 v187, v187
	v_pk_mul_f32 v[80:81], v[80:81], v[176:177]
	v_pk_mul_f32 v[82:83], v[82:83], v[178:179]
	v_pk_mul_f32 v[72:73], v[72:73], v[184:185]
	v_pk_mul_f32 v[74:75], v[74:75], v[186:187]
	v_pk_mul_f32 v[80:81], v[84:85], v[80:81]
	v_pk_mul_f32 v[82:83], v[86:87], v[82:83]
	v_pk_mul_f32 v[72:73], v[76:77], v[72:73]
	v_pk_mul_f32 v[74:75], v[78:79], v[74:75]
	v_cvt_pk_bf16_f32 v84, v80, v81
	v_cvt_pk_bf16_f32 v85, v82, v83
	v_cvt_pk_bf16_f32 v76, v72, v73
	v_cvt_pk_bf16_f32 v77, v74, v75
	s_waitcnt lgkmcnt(0)
	s_barrier
; DEVI unsigned pk_bf16(float lo, float hi) { unsigned r; asm volatile("v_cvt_pk_bf16_f32 %0, %1, %2" : "=v"(r) : "v"(lo), "v"(hi)); return r; }
; DEVI float sigmoidf_(float x) { return __builtin_amdgcn_rcpf(1.f + __expf(-x)); }
;   DEVI void operator()(int row, int colb, int fq, const f32x4& a0, const f32x4& a1, const float rinv, const bool nrm, const Pre& q) const {
;     ...
;     float v[4];
; #pragma unroll
;     for (int j = 0; j < 4; ++j) { const float a = xa[j]; v[j] = a * sigmoidf_(a) * xb[j]; }
;     uint2 o; o.x = pk_bf16(v[0], v[1]); o.y = pk_bf16(v[2], v[3]);
;     *(uint2*)(act + (size_t)row * DFF + oc) = o;
	ds_read_b128 v[152:155], v195
	ds_read_b128 v[156:159], v195 offset:1024
	ds_write_b64 v192, v[100:101] offset:49152
	ds_write_b64 v192, v[92:93] offset:51200
	ds_write_b64 v192, v[84:85] offset:53248
	ds_write_b64 v192, v[76:77] offset:55296
	v_pk_mul_f32 v[176:177], v[64:65], v[198:199]
	v_pk_mul_f32 v[178:179], v[66:67], v[198:199]
	v_pk_mul_f32 v[184:185], v[56:57], v[198:199]
	v_pk_mul_f32 v[186:187], v[58:59], v[198:199]
	v_exp_f32_e32 v176, v176
	v_exp_f32_e32 v177, v177
	v_exp_f32_e32 v178, v178
	v_exp_f32_e32 v179, v179
	v_exp_f32_e32 v184, v184
	v_exp_f32_e32 v185, v185
	v_exp_f32_e32 v186, v186
	v_exp_f32_e32 v187, v187
	v_pk_add_f32 v[176:177], v[196:197], v[176:177]
	v_pk_add_f32 v[178:179], v[196:197], v[178:179]
	v_pk_add_f32 v[184:185], v[196:197], v[184:185]
	v_pk_add_f32 v[186:187], v[196:197], v[186:187]
	v_rcp_f32_e32 v176, v176
	v_rcp_f32_e32 v177, v177
	v_rcp_f32_e32 v178, v178
	v_rcp_f32_e32 v179, v179
	v_rcp_f32_e32 v184, v184
	v_rcp_f32_e32 v185, v185
	v_rcp_f32_e32 v186, v186
	v_rcp_f32_e32 v187, v187
	v_pk_mul_f32 v[64:65], v[64:65], v[176:177]
	v_pk_mul_f32 v[66:67], v[66:67], v[178:179]
	v_pk_mul_f32 v[56:57], v[56:57], v[184:185]
	v_pk_mul_f32 v[58:59], v[58:59], v[186:187]
	v_pk_mul_f32 v[64:65], v[68:69], v[64:65]
	v_pk_mul_f32 v[66:67], v[70:71], v[66:67]
	v_pk_mul_f32 v[56:57], v[60:61], v[56:57]
	v_pk_mul_f32 v[58:59], v[62:63], v[58:59]
	v_cvt_pk_bf16_f32 v68, v64, v65
	v_cvt_pk_bf16_f32 v69, v66, v67
	v_cvt_pk_bf16_f32 v60, v56, v57
	v_cvt_pk_bf16_f32 v61, v58, v59
	v_pk_mul_f32 v[176:177], v[48:49], v[198:199]
	v_pk_mul_f32 v[178:179], v[50:51], v[198:199]
	v_pk_mul_f32 v[184:185], v[40:41], v[198:199]
	v_pk_mul_f32 v[186:187], v[42:43], v[198:199]
	v_exp_f32_e32 v176, v176
	v_exp_f32_e32 v177, v177
	v_exp_f32_e32 v178, v178
	v_exp_f32_e32 v179, v179
	v_exp_f32_e32 v184, v184
	v_exp_f32_e32 v185, v185
	v_exp_f32_e32 v186, v186
	v_exp_f32_e32 v187, v187
	v_pk_add_f32 v[176:177], v[196:197], v[176:177]
	v_pk_add_f32 v[178:179], v[196:197], v[178:179]
	v_pk_add_f32 v[184:185], v[196:197], v[184:185]
	v_pk_add_f32 v[186:187], v[196:197], v[186:187]
	v_rcp_f32_e32 v176, v176
	v_rcp_f32_e32 v177, v177
	v_rcp_f32_e32 v178, v178
	v_rcp_f32_e32 v179, v179
	v_rcp_f32_e32 v184, v184
	v_rcp_f32_e32 v185, v185
	v_rcp_f32_e32 v186, v186
	v_rcp_f32_e32 v187, v187
	v_pk_mul_f32 v[48:49], v[48:49], v[176:177]
	v_pk_mul_f32 v[50:51], v[50:51], v[178:179]
	v_pk_mul_f32 v[40:41], v[40:41], v[184:185]
	v_pk_mul_f32 v[42:43], v[42:43], v[186:187]
	v_pk_mul_f32 v[48:49], v[52:53], v[48:49]
	v_pk_mul_f32 v[50:51], v[54:55], v[50:51]
	v_pk_mul_f32 v[40:41], v[44:45], v[40:41]
	v_pk_mul_f32 v[42:43], v[46:47], v[42:43]
	v_cvt_pk_bf16_f32 v52, v48, v49
	v_cvt_pk_bf16_f32 v53, v50, v51
	v_cvt_pk_bf16_f32 v44, v40, v41
	v_cvt_pk_bf16_f32 v45, v42, v43
	s_waitcnt lgkmcnt(0)
	global_store_dwordx4 v148, v[152:155], s[44:45]
	global_store_dwordx4 v149, v[156:159], s[44:45]
	s_barrier
	ds_read_b128 v[160:163], v194 offset:49152
	ds_read_b128 v[164:167], v194 offset:50176
	ds_write_b64 v193, v[68:69]
	ds_write_b64 v193, v[60:61] offset:2048
	ds_write_b64 v193, v[52:53] offset:4096
	ds_write_b64 v193, v[44:45] offset:6144
	v_pk_mul_f32 v[176:177], v[32:33], v[198:199]
	v_pk_mul_f32 v[178:179], v[34:35], v[198:199]
	v_pk_mul_f32 v[184:185], v[24:25], v[198:199]
	v_pk_mul_f32 v[186:187], v[26:27], v[198:199]
	v_exp_f32_e32 v176, v176
	v_exp_f32_e32 v177, v177
	v_exp_f32_e32 v178, v178
	v_exp_f32_e32 v179, v179
	v_exp_f32_e32 v184, v184
	v_exp_f32_e32 v185, v185
	v_exp_f32_e32 v186, v186
	v_exp_f32_e32 v187, v187
	v_pk_add_f32 v[176:177], v[196:197], v[176:177]
	v_pk_add_f32 v[178:179], v[196:197], v[178:179]
	v_pk_add_f32 v[184:185], v[196:197], v[184:185]
	v_pk_add_f32 v[186:187], v[196:197], v[186:187]
	v_rcp_f32_e32 v176, v176
	v_rcp_f32_e32 v177, v177
	v_rcp_f32_e32 v178, v178
	v_rcp_f32_e32 v179, v179
	v_rcp_f32_e32 v184, v184
	v_rcp_f32_e32 v185, v185
	v_rcp_f32_e32 v186, v186
	v_rcp_f32_e32 v187, v187
	v_pk_mul_f32 v[32:33], v[32:33], v[176:177]
	v_pk_mul_f32 v[34:35], v[34:35], v[178:179]
	v_pk_mul_f32 v[24:25], v[24:25], v[184:185]
	v_pk_mul_f32 v[26:27], v[26:27], v[186:187]
	v_pk_mul_f32 v[32:33], v[36:37], v[32:33]
	v_pk_mul_f32 v[34:35], v[38:39], v[34:35]
	v_pk_mul_f32 v[24:25], v[28:29], v[24:25]
	v_pk_mul_f32 v[26:27], v[30:31], v[26:27]
	v_cvt_pk_bf16_f32 v36, v32, v33
	v_cvt_pk_bf16_f32 v37, v34, v35
	v_cvt_pk_bf16_f32 v28, v24, v25
	v_cvt_pk_bf16_f32 v29, v26, v27
	v_pk_mul_f32 v[176:177], v[16:17], v[198:199]
	v_pk_mul_f32 v[178:179], v[18:19], v[198:199]
	v_pk_mul_f32 v[184:185], v[8:9], v[198:199]
	v_pk_mul_f32 v[186:187], v[10:11], v[198:199]
	v_exp_f32_e32 v176, v176
	v_exp_f32_e32 v177, v177
	v_exp_f32_e32 v178, v178
	v_exp_f32_e32 v179, v179
	v_exp_f32_e32 v184, v184
	v_exp_f32_e32 v185, v185
	v_exp_f32_e32 v186, v186
	v_exp_f32_e32 v187, v187
	v_pk_add_f32 v[176:177], v[196:197], v[176:177]
	v_pk_add_f32 v[178:179], v[196:197], v[178:179]
	v_pk_add_f32 v[184:185], v[196:197], v[184:185]
	v_pk_add_f32 v[186:187], v[196:197], v[186:187]
	v_rcp_f32_e32 v176, v176
	v_rcp_f32_e32 v177, v177
	v_rcp_f32_e32 v178, v178
	v_rcp_f32_e32 v179, v179
	v_rcp_f32_e32 v184, v184
	v_rcp_f32_e32 v185, v185
	v_rcp_f32_e32 v186, v186
	v_rcp_f32_e32 v187, v187
	v_pk_mul_f32 v[16:17], v[16:17], v[176:177]
	v_pk_mul_f32 v[18:19], v[18:19], v[178:179]
	v_pk_mul_f32 v[8:9], v[8:9], v[184:185]
	v_pk_mul_f32 v[10:11], v[10:11], v[186:187]
	v_pk_mul_f32 v[16:17], v[20:21], v[16:17]
	v_pk_mul_f32 v[18:19], v[22:23], v[18:19]
	v_pk_mul_f32 v[8:9], v[12:13], v[8:9]
	v_pk_mul_f32 v[10:11], v[14:15], v[10:11]
	v_cvt_pk_bf16_f32 v20, v16, v17
	v_cvt_pk_bf16_f32 v21, v18, v19
	v_cvt_pk_bf16_f32 v12, v8, v9
	v_cvt_pk_bf16_f32 v13, v10, v11
	s_waitcnt lgkmcnt(0)
	global_store_dwordx4 v148, v[160:163], s[44:45] offset:128
	global_store_dwordx4 v149, v[164:167], s[44:45] offset:128
	s_barrier
	ds_read_b128 v[152:155], v195
	ds_read_b128 v[156:159], v195 offset:1024
	ds_write_b64 v192, v[36:37] offset:49152
	ds_write_b64 v192, v[28:29] offset:51200
	ds_write_b64 v192, v[20:21] offset:53248
	ds_write_b64 v192, v[12:13] offset:55296
	s_waitcnt lgkmcnt(0)
	global_store_dwordx4 v148, v[152:155], s[46:47]
	global_store_dwordx4 v149, v[156:159], s[46:47]
	s_barrier
	ds_read_b128 v[160:163], v194 offset:49152
	ds_read_b128 v[164:167], v194 offset:50176
	s_waitcnt lgkmcnt(0)
	global_store_dwordx4 v148, v[160:163], s[46:47] offset:128
	global_store_dwordx4 v149, v[164:167], s[46:47] offset:128
	s_mov_b32 s18, s37
	s_mov_b32 s17, s36
	s_mov_b32 s16, s40
	s_andn2_b64 vcc, exec, s[8:9]
	s_cbranch_vccz .LBB0_739
	s_branch .LBB0_675

; DEVI unsigned pk_bf16(float lo, float hi) { unsigned r; asm volatile("v_cvt_pk_bf16_f32 %0, %1, %2" : "=v"(r) : "v"(lo), "v"(hi)); return r; }
; DEVI float sigmoidf_(float x) { return __builtin_amdgcn_rcpf(1.f + __expf(-x)); }
; template <class Epi>
; DEVI void gemm_phase(const Params& p, const u16* __restrict__ A, const u16* __restrict__ Bt, const int M, const int N, const int K, const int Msplit, const Epi& epi) {
;     ...
;       for (int ai = 0; ai < 2; ++ai)
; #pragma unroll
;         for (int bj = 0; bj < 2; ++bj) {
;           const int colb = bcol + bj * HALF + wc2 * 32;
;           typename Epi::Pre pre;
;           if constexpr (Epi::NRM || Epi::SQ) epi.preload(pre, brow, colb, wr2, fr2, fq2, nrm, slcur);
; #pragma unroll
;           for (int m = 0; m < 4; ++m) {
;             const int rloc = ai * HALF + wr2 * 64 + m * 16;
;             if constexpr (Epi::SQ) epi(brow + rloc + fr2, colb, fq2, acc[ai][bj][m][0], acc[ai][bj][m][1], sq[ai * 4 + m], slcur, pre);
;             else if constexpr (Epi::TR) { float rv = 1.f; if (nrm) rv = rl[rloc + fr2]; epi(brow + rloc + fr2, colb, fq2, acc[ai][bj][m][0], acc[ai][bj][m][1], rv, nrm, pre); }
;             else { f32x4 rv = {1.f, 1.f, 1.f, 1.f}; if (nrm) rv = *(const f32x4*)(rl + rloc + fq2 * 4); epi(brow + rloc + fq2 * 4, colb, fr2, acc[ai][bj][m][0], acc[ai][bj][m][1], rv, nrm, pre); }
;           }
;   DEVI void operator()(int row, int colb, int fq, const f32x4& a0, const f32x4& a1, const float rinv, const bool nrm, const Pre& q) const {
;     const int oc = (colb >> 5) * 16 + 4 * fq;
;     f32x4 xa = a0, xb = a1;
;     if (nrm) {
; #pragma unroll
;       for (int j = 0; j < 4; ++j) { xa[j] = xa[j] * rinv + q.sa[j]; xb[j] = xb[j] * rinv + q.sb[j]; }
;     }
;     float v[4];
; #pragma unroll
;     for (int j = 0; j < 4; ++j) { const float a = xa[j]; v[j] = a * sigmoidf_(a) * xb[j]; }
;     uint2 o; o.x = pk_bf16(v[0], v[1]); o.y = pk_bf16(v[2], v[3]);
;     *(uint2*)(act + (size_t)row * DFF + oc) = o;
;   }
.LBB0_1985:
	v_mbcnt_lo_u32_b32 v208, -1, 0
	v_mbcnt_hi_u32_b32 v208, -1, v208
	s_lshr_b32 s52, s33, 6
	s_lshr_b32 s53, s52, 2
	s_and_b32 s54, s52, 3
	v_and_b32_e32 v209, 15, v208
	v_lshrrev_b32_e32 v144, 4, v208
	v_lshrrev_b32_e32 v145, 1, v144
	s_lshl_b32 s55, s54, 1
	v_or_b32_e32 v145, s55, v145
	v_and_b32_e32 v146, 7, v209
	v_xor_b32_e32 v145, v145, v146
	v_lshlrev_b32_e32 v145, 4, v145
	v_and_b32_e32 v146, 1, v144
	v_lshl_or_b32 v145, v146, 3, v145
	s_lshl_b32 s55, s53, 6
	v_add_u32_e32 v146, s55, v209
	v_lshl_add_u32 v168, v146, 7, v145
	v_add_u32_e32 v169, 0x20000, v168
	v_and_b32_e32 v147, 7, v208
	v_lshrrev_b32_e32 v150, 3, v208
	v_xor_b32_e32 v145, v147, v150
	v_lshlrev_b32_e32 v145, 4, v145
	s_lshl_b32 s55, s52, 4
	v_add_u32_e32 v146, s55, v150
	v_lshl_add_u32 v170, v146, 7, v145
	v_add_u32_e32 v171, 0x20000, v170
	v_mul_u32_u24_e32 v146, 0x1600, v146
	v_lshl_add_u32 v172, v147, 4, v146
	v_add_u32_e32 v173, 0xb000, v172
	v_mov_b32_e32 v148, 1.0
	v_mov_b32_e32 v149, 1.0
	v_mov_b32_e32 v206, 0xbfb8aa3b
	v_mov_b32_e32 v207, 0xbfb8aa3b
	s_mul_i32 s54, s20, 0x1600
	s_add_u32 s54, s54, s22
	s_add_u32 s44, s60, s54
	s_addc_u32 s45, s61, 0
	s_add_u32 s46, s44, 0xb0000
	s_addc_u32 s47, s45, 0
	s_mov_b32 s21, s37
	s_mov_b32 s16, s40
	s_mov_b32 s20, s41
	v_pk_mul_f32 v[128:129], v[120:121], v[206:207]
	v_pk_mul_f32 v[130:131], v[122:123], v[206:207]
	v_pk_mul_f32 v[136:137], v[112:113], v[206:207]
	v_pk_mul_f32 v[138:139], v[114:115], v[206:207]
	v_exp_f32_e32 v128, v128
	v_exp_f32_e32 v129, v129
	v_exp_f32_e32 v130, v130
	v_exp_f32_e32 v131, v131
	v_exp_f32_e32 v136, v136
	v_exp_f32_e32 v137, v137
	v_exp_f32_e32 v138, v138
	v_exp_f32_e32 v139, v139
	v_pk_add_f32 v[128:129], v[148:149], v[128:129]
	v_pk_add_f32 v[130:131], v[148:149], v[130:131]
	v_pk_add_f32 v[136:137], v[148:149], v[136:137]
	v_pk_add_f32 v[138:139], v[148:149], v[138:139]
	v_rcp_f32_e32 v128, v128
	v_rcp_f32_e32 v129, v129
	v_rcp_f32_e32 v130, v130
	v_rcp_f32_e32 v131, v131
	v_rcp_f32_e32 v136, v136
	v_rcp_f32_e32 v137, v137
	v_rcp_f32_e32 v138, v138
	v_rcp_f32_e32 v139, v139
	v_pk_mul_f32 v[120:121], v[120:121], v[128:129]
	v_pk_mul_f32 v[122:123], v[122:123], v[130:131]
	v_pk_mul_f32 v[112:113], v[112:113], v[136:137]
	v_pk_mul_f32 v[114:115], v[114:115], v[138:139]
	v_pk_mul_f32 v[120:121], v[124:125], v[120:121]
	v_pk_mul_f32 v[122:123], v[126:127], v[122:123]
	v_pk_mul_f32 v[112:113], v[116:117], v[112:113]
	v_pk_mul_f32 v[114:115], v[118:119], v[114:115]
	v_cvt_pk_bf16_f32 v124, v120, v121
	v_cvt_pk_bf16_f32 v125, v122, v123
	v_cvt_pk_bf16_f32 v116, v112, v113
	v_cvt_pk_bf16_f32 v117, v114, v115
	v_pk_mul_f32 v[128:129], v[104:105], v[206:207]
	v_pk_mul_f32 v[130:131], v[106:107], v[206:207]
	v_pk_mul_f32 v[136:137], v[96:97], v[206:207]
	v_pk_mul_f32 v[138:139], v[98:99], v[206:207]
	v_exp_f32_e32 v128, v128
	v_exp_f32_e32 v129, v129
	v_exp_f32_e32 v130, v130
	v_exp_f32_e32 v131, v131
	v_exp_f32_e32 v136, v136
	v_exp_f32_e32 v137, v137
	v_exp_f32_e32 v138, v138
	v_exp_f32_e32 v139, v139
	v_pk_add_f32 v[128:129], v[148:149], v[128:129]
	v_pk_add_f32 v[130:131], v[148:149], v[130:131]
	v_pk_add_f32 v[136:137], v[148:149], v[136:137]
	v_pk_add_f32 v[138:139], v[148:149], v[138:139]
	v_rcp_f32_e32 v128, v128
	v_rcp_f32_e32 v129, v129
	v_rcp_f32_e32 v130, v130
	v_rcp_f32_e32 v131, v131
	v_rcp_f32_e32 v136, v136
	v_rcp_f32_e32 v137, v137
	v_rcp_f32_e32 v138, v138
	v_rcp_f32_e32 v139, v139
	v_pk_mul_f32 v[104:105], v[104:105], v[128:129]
	v_pk_mul_f32 v[106:107], v[106:107], v[130:131]
	v_pk_mul_f32 v[96:97], v[96:97], v[136:137]
	v_pk_mul_f32 v[98:99], v[98:99], v[138:139]
	v_pk_mul_f32 v[104:105], v[108:109], v[104:105]
	v_pk_mul_f32 v[106:107], v[110:111], v[106:107]
	v_pk_mul_f32 v[96:97], v[100:101], v[96:97]
	v_pk_mul_f32 v[98:99], v[102:103], v[98:99]
	v_cvt_pk_bf16_f32 v108, v104, v105
	v_cvt_pk_bf16_f32 v109, v106, v107
	v_cvt_pk_bf16_f32 v100, v96, v97
	v_cvt_pk_bf16_f32 v101, v98, v99
	ds_write_b64 v169, v[124:125]
	ds_write_b64 v169, v[116:117] offset:2048
	ds_write_b64 v169, v[108:109] offset:4096
	ds_write_b64 v169, v[100:101] offset:6144
	v_pk_mul_f32 v[128:129], v[88:89], v[206:207]
	v_pk_mul_f32 v[130:131], v[90:91], v[206:207]
	v_pk_mul_f32 v[136:137], v[80:81], v[206:207]
	v_pk_mul_f32 v[138:139], v[82:83], v[206:207]
	v_exp_f32_e32 v128, v128
	v_exp_f32_e32 v129, v129
	v_exp_f32_e32 v130, v130
	v_exp_f32_e32 v131, v131
	v_exp_f32_e32 v136, v136
	v_exp_f32_e32 v137, v137
	v_exp_f32_e32 v138, v138
	v_exp_f32_e32 v139, v139
	v_pk_add_f32 v[128:129], v[148:149], v[128:129]
	v_pk_add_f32 v[130:131], v[148:149], v[130:131]
	v_pk_add_f32 v[136:137], v[148:149], v[136:137]
	v_pk_add_f32 v[138:139], v[148:149], v[138:139]
	v_rcp_f32_e32 v128, v128
	v_rcp_f32_e32 v129, v129
	v_rcp_f32_e32 v130, v130
	v_rcp_f32_e32 v131, v131
	v_rcp_f32_e32 v136, v136
	v_rcp_f32_e32 v137, v137
	v_rcp_f32_e32 v138, v138
	v_rcp_f32_e32 v139, v139
	v_pk_mul_f32 v[88:89], v[88:89], v[128:129]
	v_pk_mul_f32 v[90:91], v[90:91], v[130:131]
	v_pk_mul_f32 v[80:81], v[80:81], v[136:137]
	v_pk_mul_f32 v[82:83], v[82:83], v[138:139]
	v_pk_mul_f32 v[88:89], v[92:93], v[88:89]
	v_pk_mul_f32 v[90:91], v[94:95], v[90:91]
	v_pk_mul_f32 v[80:81], v[84:85], v[80:81]
	v_pk_mul_f32 v[82:83], v[86:87], v[82:83]
	v_cvt_pk_bf16_f32 v92, v88, v89
	v_cvt_pk_bf16_f32 v93, v90, v91
	v_cvt_pk_bf16_f32 v84, v80, v81
	v_cvt_pk_bf16_f32 v85, v82, v83
	v_pk_mul_f32 v[128:129], v[72:73], v[206:207]
	v_pk_mul_f32 v[130:131], v[74:75], v[206:207]
	v_pk_mul_f32 v[136:137], v[64:65], v[206:207]
	v_pk_mul_f32 v[138:139], v[66:67], v[206:207]
	v_exp_f32_e32 v128, v128
	v_exp_f32_e32 v129, v129
	v_exp_f32_e32 v130, v130
	v_exp_f32_e32 v131, v131
	v_exp_f32_e32 v136, v136
	v_exp_f32_e32 v137, v137
	v_exp_f32_e32 v138, v138
	v_exp_f32_e32 v139, v139
	v_pk_add_f32 v[128:129], v[148:149], v[128:129]
	v_pk_add_f32 v[130:131], v[148:149], v[130:131]
	v_pk_add_f32 v[136:137], v[148:149], v[136:137]
	v_pk_add_f32 v[138:139], v[148:149], v[138:139]
	v_rcp_f32_e32 v128, v128
	v_rcp_f32_e32 v129, v129
	v_rcp_f32_e32 v130, v130
	v_rcp_f32_e32 v131, v131
	v_rcp_f32_e32 v136, v136
	v_rcp_f32_e32 v137, v137
	v_rcp_f32_e32 v138, v138
	v_rcp_f32_e32 v139, v139
	v_pk_mul_f32 v[72:73], v[72:73], v[128:129]
	v_pk_mul_f32 v[74:75], v[74:75], v[130:131]
	v_pk_mul_f32 v[64:65], v[64:65], v[136:137]
	v_pk_mul_f32 v[66:67], v[66:67], v[138:139]
	v_pk_mul_f32 v[72:73], v[76:77], v[72:73]
	v_pk_mul_f32 v[74:75], v[78:79], v[74:75]
	v_pk_mul_f32 v[64:65], v[68:69], v[64:65]
	v_pk_mul_f32 v[66:67], v[70:71], v[66:67]
	v_cvt_pk_bf16_f32 v76, v72, v73
	v_cvt_pk_bf16_f32 v77, v74, v75
	v_cvt_pk_bf16_f32 v68, v64, v65
	v_cvt_pk_bf16_f32 v69, v66, v67
	s_waitcnt lgkmcnt(0)
	s_barrier
; DEVI unsigned pk_bf16(float lo, float hi) { unsigned r; asm volatile("v_cvt_pk_bf16_f32 %0, %1, %2" : "=v"(r) : "v"(lo), "v"(hi)); return r; }
; DEVI float sigmoidf_(float x) { return __builtin_amdgcn_rcpf(1.f + __expf(-x)); }
; template <class Epi>
; DEVI void gemm_phase(const Params& p, const u16* __restrict__ A, const u16* __restrict__ Bt, const int M, const int N, const int K, const int Msplit, const Epi& epi) {
;     ...
;       for (int ai = 0; ai < 2; ++ai)
; #pragma unroll
;         for (int bj = 0; bj < 2; ++bj) {
;           const int colb = bcol + bj * HALF + wc2 * 32;
;           typename Epi::Pre pre;
;           if constexpr (Epi::NRM || Epi::SQ) epi.preload(pre, brow, colb, wr2, fr2, fq2, nrm, slcur);
; #pragma unroll
;           for (int m = 0; m < 4; ++m) {
;             const int rloc = ai * HALF + wr2 * 64 + m * 16;
;             if constexpr (Epi::SQ) epi(brow + rloc + fr2, colb, fq2, acc[ai][bj][m][0], acc[ai][bj][m][1], sq[ai * 4 + m], slcur, pre);
;             else if constexpr (Epi::TR) { float rv = 1.f; if (nrm) rv = rl[rloc + fr2]; epi(brow + rloc + fr2, colb, fq2, acc[ai][bj][m][0], acc[ai][bj][m][1], rv, nrm, pre); }
;             else { f32x4 rv = {1.f, 1.f, 1.f, 1.f}; if (nrm) rv = *(const f32x4*)(rl + rloc + fq2 * 4); epi(brow + rloc + fq2 * 4, colb, fr2, acc[ai][bj][m][0], acc[ai][bj][m][1], rv, nrm, pre); }
;           }
;   DEVI void operator()(int row, int colb, int fq, const f32x4& a0, const f32x4& a1, const float rinv, const bool nrm, const Pre& q) const {
;     const int oc = (colb >> 5) * 16 + 4 * fq;
;     f32x4 xa = a0, xb = a1;
;     if (nrm) {
; #pragma unroll
;       for (int j = 0; j < 4; ++j) { xa[j] = xa[j] * rinv + q.sa[j]; xb[j] = xb[j] * rinv + q.sb[j]; }
;     }
;     float v[4];
; #pragma unroll
;     for (int j = 0; j < 4; ++j) { const float a = xa[j]; v[j] = a * sigmoidf_(a) * xb[j]; }
;     uint2 o; o.x = pk_bf16(v[0], v[1]); o.y = pk_bf16(v[2], v[3]);
;     *(uint2*)(act + (size_t)row * DFF + oc) = o;
;   }
	ds_read_b128 v[152:155], v171
	ds_read_b128 v[156:159], v171 offset:1024
	ds_write_b64 v168, v[92:93] offset:49152
	ds_write_b64 v168, v[84:85] offset:51200
	ds_write_b64 v168, v[76:77] offset:53248
	ds_write_b64 v168, v[68:69] offset:55296
	v_pk_mul_f32 v[128:129], v[56:57], v[206:207]
	v_pk_mul_f32 v[130:131], v[58:59], v[206:207]
	v_pk_mul_f32 v[136:137], v[48:49], v[206:207]
	v_pk_mul_f32 v[138:139], v[50:51], v[206:207]
	v_exp_f32_e32 v128, v128
	v_exp_f32_e32 v129, v129
	v_exp_f32_e32 v130, v130
	v_exp_f32_e32 v131, v131
	v_exp_f32_e32 v136, v136
	v_exp_f32_e32 v137, v137
	v_exp_f32_e32 v138, v138
	v_exp_f32_e32 v139, v139
	v_pk_add_f32 v[128:129], v[148:149], v[128:129]
	v_pk_add_f32 v[130:131], v[148:149], v[130:131]
	v_pk_add_f32 v[136:137], v[148:149], v[136:137]
	v_pk_add_f32 v[138:139], v[148:149], v[138:139]
	v_rcp_f32_e32 v128, v128
	v_rcp_f32_e32 v129, v129
	v_rcp_f32_e32 v130, v130
	v_rcp_f32_e32 v131, v131
	v_rcp_f32_e32 v136, v136
	v_rcp_f32_e32 v137, v137
	v_rcp_f32_e32 v138, v138
	v_rcp_f32_e32 v139, v139
	v_pk_mul_f32 v[56:57], v[56:57], v[128:129]
	v_pk_mul_f32 v[58:59], v[58:59], v[130:131]
	v_pk_mul_f32 v[48:49], v[48:49], v[136:137]
	v_pk_mul_f32 v[50:51], v[50:51], v[138:139]
	v_pk_mul_f32 v[56:57], v[60:61], v[56:57]
	v_pk_mul_f32 v[58:59], v[62:63], v[58:59]
	v_pk_mul_f32 v[48:49], v[52:53], v[48:49]
	v_pk_mul_f32 v[50:51], v[54:55], v[50:51]
	v_cvt_pk_bf16_f32 v60, v56, v57
	v_cvt_pk_bf16_f32 v61, v58, v59
	v_cvt_pk_bf16_f32 v52, v48, v49
	v_cvt_pk_bf16_f32 v53, v50, v51
	v_pk_mul_f32 v[128:129], v[40:41], v[206:207]
	v_pk_mul_f32 v[130:131], v[42:43], v[206:207]
	v_pk_mul_f32 v[136:137], v[32:33], v[206:207]
	v_pk_mul_f32 v[138:139], v[34:35], v[206:207]
	v_exp_f32_e32 v128, v128
	v_exp_f32_e32 v129, v129
	v_exp_f32_e32 v130, v130
	v_exp_f32_e32 v131, v131
	v_exp_f32_e32 v136, v136
	v_exp_f32_e32 v137, v137
	v_exp_f32_e32 v138, v138
	v_exp_f32_e32 v139, v139
	v_pk_add_f32 v[128:129], v[148:149], v[128:129]
	v_pk_add_f32 v[130:131], v[148:149], v[130:131]
	v_pk_add_f32 v[136:137], v[148:149], v[136:137]
	v_pk_add_f32 v[138:139], v[148:149], v[138:139]
	v_rcp_f32_e32 v128, v128
	v_rcp_f32_e32 v129, v129
	v_rcp_f32_e32 v130, v130
	v_rcp_f32_e32 v131, v131
	v_rcp_f32_e32 v136, v136
	v_rcp_f32_e32 v137, v137
	v_rcp_f32_e32 v138, v138
	v_rcp_f32_e32 v139, v139
	v_pk_mul_f32 v[40:41], v[40:41], v[128:129]
	v_pk_mul_f32 v[42:43], v[42:43], v[130:131]
	v_pk_mul_f32 v[32:33], v[32:33], v[136:137]
	v_pk_mul_f32 v[34:35], v[34:35], v[138:139]
	v_pk_mul_f32 v[40:41], v[44:45], v[40:41]
	v_pk_mul_f32 v[42:43], v[46:47], v[42:43]
	v_pk_mul_f32 v[32:33], v[36:37], v[32:33]
	v_pk_mul_f32 v[34:35], v[38:39], v[34:35]
	v_cvt_pk_bf16_f32 v44, v40, v41
	v_cvt_pk_bf16_f32 v45, v42, v43
	v_cvt_pk_bf16_f32 v36, v32, v33
	v_cvt_pk_bf16_f32 v37, v34, v35
	s_waitcnt lgkmcnt(0)
	global_store_dwordx4 v172, v[152:155], s[44:45]
	global_store_dwordx4 v173, v[156:159], s[44:45]
	s_barrier
	ds_read_b128 v[160:163], v170 offset:49152
	ds_read_b128 v[164:167], v170 offset:50176
	ds_write_b64 v169, v[60:61]
	ds_write_b64 v169, v[52:53] offset:2048
	ds_write_b64 v169, v[44:45] offset:4096
	ds_write_b64 v169, v[36:37] offset:6144
	v_pk_mul_f32 v[128:129], v[24:25], v[206:207]
	v_pk_mul_f32 v[130:131], v[26:27], v[206:207]
	v_pk_mul_f32 v[136:137], v[16:17], v[206:207]
	v_pk_mul_f32 v[138:139], v[18:19], v[206:207]
	v_exp_f32_e32 v128, v128
	v_exp_f32_e32 v129, v129
	v_exp_f32_e32 v130, v130
	v_exp_f32_e32 v131, v131
	v_exp_f32_e32 v136, v136
	v_exp_f32_e32 v137, v137
	v_exp_f32_e32 v138, v138
	v_exp_f32_e32 v139, v139
	v_pk_add_f32 v[128:129], v[148:149], v[128:129]
	v_pk_add_f32 v[130:131], v[148:149], v[130:131]
	v_pk_add_f32 v[136:137], v[148:149], v[136:137]
	v_pk_add_f32 v[138:139], v[148:149], v[138:139]
	v_rcp_f32_e32 v128, v128
	v_rcp_f32_e32 v129, v129
	v_rcp_f32_e32 v130, v130
	v_rcp_f32_e32 v131, v131
	v_rcp_f32_e32 v136, v136
	v_rcp_f32_e32 v137, v137
	v_rcp_f32_e32 v138, v138
	v_rcp_f32_e32 v139, v139
	v_pk_mul_f32 v[24:25], v[24:25], v[128:129]
	v_pk_mul_f32 v[26:27], v[26:27], v[130:131]
	v_pk_mul_f32 v[16:17], v[16:17], v[136:137]
	v_pk_mul_f32 v[18:19], v[18:19], v[138:139]
	v_pk_mul_f32 v[24:25], v[28:29], v[24:25]
	v_pk_mul_f32 v[26:27], v[30:31], v[26:27]
	v_pk_mul_f32 v[16:17], v[20:21], v[16:17]
	v_pk_mul_f32 v[18:19], v[22:23], v[18:19]
	v_cvt_pk_bf16_f32 v28, v24, v25
	v_cvt_pk_bf16_f32 v29, v26, v27
	v_cvt_pk_bf16_f32 v20, v16, v17
	v_cvt_pk_bf16_f32 v21, v18, v19
	v_pk_mul_f32 v[128:129], v[8:9], v[206:207]
	v_pk_mul_f32 v[130:131], v[10:11], v[206:207]
	v_pk_mul_f32 v[136:137], v[0:1], v[206:207]
	v_pk_mul_f32 v[138:139], v[2:3], v[206:207]
	v_exp_f32_e32 v128, v128
	v_exp_f32_e32 v129, v129
	v_exp_f32_e32 v130, v130
	v_exp_f32_e32 v131, v131
	v_exp_f32_e32 v136, v136
	v_exp_f32_e32 v137, v137
	v_exp_f32_e32 v138, v138
	v_exp_f32_e32 v139, v139
	v_pk_add_f32 v[128:129], v[148:149], v[128:129]
	v_pk_add_f32 v[130:131], v[148:149], v[130:131]
	v_pk_add_f32 v[136:137], v[148:149], v[136:137]
	v_pk_add_f32 v[138:139], v[148:149], v[138:139]
	v_rcp_f32_e32 v128, v128
	v_rcp_f32_e32 v129, v129
	v_rcp_f32_e32 v130, v130
	v_rcp_f32_e32 v131, v131
	v_rcp_f32_e32 v136, v136
	v_rcp_f32_e32 v137, v137
	v_rcp_f32_e32 v138, v138
	v_rcp_f32_e32 v139, v139
	v_pk_mul_f32 v[8:9], v[8:9], v[128:129]
	v_pk_mul_f32 v[10:11], v[10:11], v[130:131]
	v_pk_mul_f32 v[0:1], v[0:1], v[136:137]
	v_pk_mul_f32 v[2:3], v[2:3], v[138:139]
	v_pk_mul_f32 v[8:9], v[12:13], v[8:9]
	v_pk_mul_f32 v[10:11], v[14:15], v[10:11]
	v_pk_mul_f32 v[0:1], v[4:5], v[0:1]
	v_pk_mul_f32 v[2:3], v[6:7], v[2:3]
	v_cvt_pk_bf16_f32 v12, v8, v9
	v_cvt_pk_bf16_f32 v13, v10, v11
	v_cvt_pk_bf16_f32 v4, v0, v1
	v_cvt_pk_bf16_f32 v5, v2, v3
	s_waitcnt lgkmcnt(0)
	global_store_dwordx4 v172, v[160:163], s[44:45] offset:128
	global_store_dwordx4 v173, v[164:167], s[44:45] offset:128
	s_barrier
	ds_read_b128 v[152:155], v171
	ds_read_b128 v[156:159], v171 offset:1024
	ds_write_b64 v168, v[28:29] offset:49152
	ds_write_b64 v168, v[20:21] offset:51200
	ds_write_b64 v168, v[12:13] offset:53248
	ds_write_b64 v168, v[4:5] offset:55296
	s_waitcnt lgkmcnt(0)
	global_store_dwordx4 v172, v[152:155], s[46:47]
	global_store_dwordx4 v173, v[156:159], s[46:47]
	s_barrier
	ds_read_b128 v[160:163], v170 offset:49152
	ds_read_b128 v[164:167], v170 offset:50176
	s_waitcnt lgkmcnt(0)
	global_store_dwordx4 v172, v[160:163], s[46:47] offset:128
	global_store_dwordx4 v173, v[164:167], s[46:47] offset:128
	s_andn2_b64 vcc, exec, s[10:11]
	s_cbranch_vccz .LBB0_2006

; #define WAIT_V(n) asm volatile("s_waitcnt vmcnt(" #n ")" ::: "memory")
; template <class Epi>
; DEVI void gemm_phase(const Params& p, const u16* __restrict__ A, const u16* __restrict__ Bt, const int M, const int N, const int K, const int Msplit, const Epi& epi) {
;     ...
;     if (it == 0) { WAIT_V(0); } else { if constexpr (Epi::NST == 16) WAIT_V(16); else if constexpr (Epi::NST == 32) WAIT_V(32); else WAIT_V(0); }
.LBB0_1988:
	s_cmp_lg_u32 s21, 0
	s_cbranch_scc0 .LBB0_2005
	s_waitcnt vmcnt(8)
	s_cbranch_execnz .LBB0_1991
